# grid barrier: non-leaders poll top-level generation directly (one hop less per seam)
# speedup vs baseline: 1.0086x; 1.0010x over previous
.LBB0_90:
	s_or_b64 exec, exec, s[8:9]
	v_cvt_f32_u32_e32 v4, v2
	s_waitcnt vmcnt(0)
	v_readfirstlane_b32 s3, v3
	v_sub_u32_e32 v3, 0, v2
	v_rcp_iflag_f32_e32 v4, v4
	v_add_u32_e32 v5, s3, v1
	v_mul_f32_e32 v4, 0x4f7ffffe, v4
	v_cvt_u32_f32_e32 v4, v4
	v_mul_lo_u32 v1, v3, v4
	v_mul_hi_u32 v1, v4, v1
	v_add_u32_e32 v1, v4, v1
	v_mul_hi_u32 v1, v5, v1
	v_mul_lo_u32 v3, v1, v2
	v_sub_u32_e32 v3, v5, v3
	v_add_u32_e32 v4, 1, v1
	v_cmp_ge_u32_e32 vcc, v3, v2
	s_nop 1
	v_cndmask_b32_e32 v1, v1, v4, vcc
	v_sub_u32_e32 v4, v3, v2
	v_cndmask_b32_e32 v3, v3, v4, vcc
	v_add_u32_e32 v4, 1, v1
	v_cmp_ge_u32_e32 vcc, v3, v2
	v_add_u32_e32 v3, 1, v5
	s_nop 0
	v_cndmask_b32_e32 v1, v1, v4, vcc
	v_mul_lo_u32 v4, v2, v1
	v_add_u32_e32 v2, v4, v2
	v_cmp_ne_u32_e32 vcc, v3, v2
	s_and_saveexec_b64 s[6:7], vcc
	s_xor_b64 s[6:7], exec, s[6:7]
	s_cbranch_execz .LBB0_104
	s_waitcnt lgkmcnt(0)
	v_mov_b32_e32 v0, 0x3100
	global_load_dword v0, v0, s[52:53] offset:1024 sc1
	s_add_u32 s10, s52, 0x3500
	s_addc_u32 s11, s53, 0
	s_waitcnt vmcnt(0)
	v_cmp_eq_u32_e32 vcc, v0, v1
	s_and_saveexec_b64 s[8:9], vcc
	s_cbranch_execz .LBB0_103
	s_mov_b32 s3, 1
	s_mov_b64 s[12:13], 0
	v_mov_b32_e32 v0, 0
	s_branch .LBB0_94

.LBB0_192:
	s_or_b64 exec, exec, s[10:11]
	v_cvt_f32_u32_e32 v4, v2
	s_waitcnt vmcnt(0)
	v_readfirstlane_b32 s3, v3
	v_sub_u32_e32 v3, 0, v2
	v_rcp_iflag_f32_e32 v4, v4
	v_add_u32_e32 v5, s3, v1
	v_mul_f32_e32 v4, 0x4f7ffffe, v4
	v_cvt_u32_f32_e32 v4, v4
	v_mul_lo_u32 v1, v3, v4
	v_mul_hi_u32 v1, v4, v1
	v_add_u32_e32 v1, v4, v1
	v_mul_hi_u32 v1, v5, v1
	v_mul_lo_u32 v3, v1, v2
	v_sub_u32_e32 v3, v5, v3
	v_add_u32_e32 v4, 1, v1
	v_cmp_ge_u32_e32 vcc, v3, v2
	s_nop 1
	v_cndmask_b32_e32 v1, v1, v4, vcc
	v_sub_u32_e32 v4, v3, v2
	v_cndmask_b32_e32 v3, v3, v4, vcc
	v_add_u32_e32 v4, 1, v1
	v_cmp_ge_u32_e32 vcc, v3, v2
	v_add_u32_e32 v3, 1, v5
	s_nop 0
	v_cndmask_b32_e32 v1, v1, v4, vcc
	v_mul_lo_u32 v4, v2, v1
	v_add_u32_e32 v2, v4, v2
	v_cmp_ne_u32_e32 vcc, v3, v2
	s_and_saveexec_b64 s[8:9], vcc
	s_xor_b64 s[8:9], exec, s[8:9]
	s_cbranch_execz .LBB0_206
	s_waitcnt lgkmcnt(0)
	v_mov_b32_e32 v0, 0x3100
	global_load_dword v0, v0, s[52:53] offset:1024 sc1
	s_add_u32 s12, s52, 0x3500
	s_addc_u32 s13, s53, 0
	s_waitcnt vmcnt(0)
	v_cmp_eq_u32_e32 vcc, v0, v1
	s_and_saveexec_b64 s[10:11], vcc
	s_cbranch_execz .LBB0_205
	s_mov_b32 s3, 1
	s_mov_b64 s[16:17], 0
	v_mov_b32_e32 v0, 0
	s_branch .LBB0_196

.LBB0_313:
	s_or_b64 exec, exec, s[12:13]
	v_cvt_f32_u32_e32 v4, v2
	s_waitcnt vmcnt(0)
	v_readfirstlane_b32 s10, v3
	v_sub_u32_e32 v3, 0, v2
	v_rcp_iflag_f32_e32 v4, v4
	v_add_u32_e32 v5, s10, v1
	v_mul_f32_e32 v4, 0x4f7ffffe, v4
	v_cvt_u32_f32_e32 v4, v4
	v_mul_lo_u32 v1, v3, v4
	v_mul_hi_u32 v1, v4, v1
	v_add_u32_e32 v1, v4, v1
	v_mul_hi_u32 v1, v5, v1
	v_mul_lo_u32 v3, v1, v2
	v_sub_u32_e32 v3, v5, v3
	v_add_u32_e32 v4, 1, v1
	v_cmp_ge_u32_e32 vcc, v3, v2
	s_nop 1
	v_cndmask_b32_e32 v1, v1, v4, vcc
	v_sub_u32_e32 v4, v3, v2
	v_cndmask_b32_e32 v3, v3, v4, vcc
	v_add_u32_e32 v4, 1, v1
	v_cmp_ge_u32_e32 vcc, v3, v2
	v_add_u32_e32 v3, 1, v5
	s_nop 0
	v_cndmask_b32_e32 v1, v1, v4, vcc
	v_mul_lo_u32 v4, v2, v1
	v_add_u32_e32 v2, v4, v2
	v_cmp_ne_u32_e32 vcc, v3, v2
	s_and_saveexec_b64 s[10:11], vcc
	s_xor_b64 s[10:11], exec, s[10:11]
	s_cbranch_execz .LBB0_327
	s_waitcnt lgkmcnt(0)
	v_mov_b32_e32 v0, 0x3100
	global_load_dword v0, v0, s[52:53] offset:1024 sc1
	s_add_u32 s16, s52, 0x3500
	s_addc_u32 s17, s53, 0
	s_waitcnt vmcnt(0)
	v_cmp_eq_u32_e32 vcc, v0, v1
	s_and_saveexec_b64 s[12:13], vcc
	s_cbranch_execz .LBB0_326
	s_mov_b32 s14, 1
	s_mov_b64 s[18:19], 0
	v_mov_b32_e32 v0, 0
	s_branch .LBB0_317

.LBB0_486:
	s_or_b64 exec, exec, s[20:21]
	v_cvt_f32_u32_e32 v7, v3
	s_waitcnt vmcnt(0)
	v_readfirstlane_b32 s14, v6
	v_sub_u32_e32 v6, 0, v3
	v_rcp_iflag_f32_e32 v7, v7
	v_add_u32_e32 v8, s14, v1
	v_mul_f32_e32 v7, 0x4f7ffffe, v7
	v_cvt_u32_f32_e32 v7, v7
	v_mul_lo_u32 v1, v6, v7
	v_mul_hi_u32 v1, v7, v1
	v_add_u32_e32 v1, v7, v1
	v_mul_hi_u32 v1, v8, v1
	v_mul_lo_u32 v6, v1, v3
	v_sub_u32_e32 v6, v8, v6
	v_add_u32_e32 v7, 1, v1
	v_cmp_ge_u32_e32 vcc, v6, v3
	s_nop 1
	v_cndmask_b32_e32 v1, v1, v7, vcc
	v_sub_u32_e32 v7, v6, v3
	v_cndmask_b32_e32 v6, v6, v7, vcc
	v_add_u32_e32 v7, 1, v1
	v_cmp_ge_u32_e32 vcc, v6, v3
	v_add_u32_e32 v6, 1, v8
	s_nop 0
	v_cndmask_b32_e32 v1, v1, v7, vcc
	v_mul_lo_u32 v7, v3, v1
	v_add_u32_e32 v3, v7, v3
	v_cmp_ne_u32_e32 vcc, v6, v3
	s_and_saveexec_b64 s[14:15], vcc
	s_xor_b64 s[16:17], exec, s[14:15]
	s_cbranch_execz .LBB0_500
	s_waitcnt lgkmcnt(0)
	v_mov_b32_e32 v0, 0x3100
	global_load_dword v0, v0, s[52:53] offset:1024 sc1
	s_add_u32 s22, s52, 0x3500
	s_addc_u32 s23, s53, 0
	s_waitcnt vmcnt(0)
	v_cmp_eq_u32_e32 vcc, v0, v1
	s_and_saveexec_b64 s[20:21], vcc
	s_cbranch_execz .LBB0_499
	s_mov_b32 s14, 1
	s_mov_b64 s[24:25], 0
	v_mov_b32_e32 v0, 0
	s_branch .LBB0_490

.LBB0_706:
	s_or_b64 exec, exec, s[10:11]
	v_cvt_f32_u32_e32 v4, v2
	s_waitcnt vmcnt(0)
	v_readfirstlane_b32 s8, v3
	v_sub_u32_e32 v3, 0, v2
	v_rcp_iflag_f32_e32 v4, v4
	v_add_u32_e32 v5, s8, v1
	v_mul_f32_e32 v4, 0x4f7ffffe, v4
	v_cvt_u32_f32_e32 v4, v4
	v_mul_lo_u32 v1, v3, v4
	v_mul_hi_u32 v1, v4, v1
	v_add_u32_e32 v1, v4, v1
	v_mul_hi_u32 v1, v5, v1
	v_mul_lo_u32 v3, v1, v2
	v_sub_u32_e32 v3, v5, v3
	v_add_u32_e32 v4, 1, v1
	v_cmp_ge_u32_e32 vcc, v3, v2
	s_nop 1
	v_cndmask_b32_e32 v1, v1, v4, vcc
	v_sub_u32_e32 v4, v3, v2
	v_cndmask_b32_e32 v3, v3, v4, vcc
	v_add_u32_e32 v4, 1, v1
	v_cmp_ge_u32_e32 vcc, v3, v2
	v_add_u32_e32 v3, 1, v5
	s_nop 0
	v_cndmask_b32_e32 v1, v1, v4, vcc
	v_mul_lo_u32 v4, v2, v1
	v_add_u32_e32 v2, v4, v2
	v_cmp_ne_u32_e32 vcc, v3, v2
	s_and_saveexec_b64 s[8:9], vcc
	s_xor_b64 s[8:9], exec, s[8:9]
	s_cbranch_execz .LBB0_720
	s_waitcnt lgkmcnt(0)
	v_mov_b32_e32 v0, 0x3100
	global_load_dword v0, v0, s[52:53] offset:1024 sc1
	s_add_u32 s12, s52, 0x3500
	s_addc_u32 s13, s53, 0
	s_waitcnt vmcnt(0)
	v_cmp_eq_u32_e32 vcc, v0, v1
	s_and_saveexec_b64 s[10:11], vcc
	s_cbranch_execz .LBB0_719
	s_mov_b32 s24, 1
	s_mov_b64 s[14:15], 0
	v_mov_b32_e32 v0, 0
	s_branch .LBB0_710
